# grid barrier: non-leader workgroups poll the cross-XCD release generation directly instead of the per-XCD generation their leader bumps after seeing it (6 of 7 barrier sites)
# speedup vs baseline: 1.0055x; 1.0055x over previous
.LBB0_386:
	s_or_b64 exec, exec, s[14:15]
	v_cvt_f32_u32_e32 v5, v3
	s_waitcnt vmcnt(0)
	v_readfirstlane_b32 s12, v4
	v_sub_u32_e32 v4, 0, v3
	v_rcp_iflag_f32_e32 v5, v5
	v_add_u32_e32 v6, s12, v0
	v_mul_f32_e32 v5, 0x4f7ffffe, v5
	v_cvt_u32_f32_e32 v5, v5
	v_mul_lo_u32 v0, v4, v5
	v_mul_hi_u32 v0, v5, v0
	v_add_u32_e32 v0, v5, v0
	v_mul_hi_u32 v0, v6, v0
	v_mul_lo_u32 v4, v0, v3
	v_sub_u32_e32 v4, v6, v4
	v_add_u32_e32 v5, 1, v0
	v_cmp_ge_u32_e32 vcc, v4, v3
	s_nop 1
	v_cndmask_b32_e32 v0, v0, v5, vcc
	v_sub_u32_e32 v5, v4, v3
	v_cndmask_b32_e32 v4, v4, v5, vcc
	v_add_u32_e32 v5, 1, v0
	v_cmp_ge_u32_e32 vcc, v4, v3
	v_add_u32_e32 v4, 1, v6
	s_nop 0
	v_cndmask_b32_e32 v0, v0, v5, vcc
	v_mul_lo_u32 v5, v3, v0
	v_add_u32_e32 v3, v5, v3
	v_cmp_ne_u32_e32 vcc, v4, v3
	s_and_saveexec_b64 s[12:13], vcc
	s_xor_b64 s[12:13], exec, s[12:13]
	s_cbranch_execz .LBB0_400
	s_waitcnt lgkmcnt(0)
	s_add_u32 s18, s8, 0xf104500
	s_addc_u32 s19, s9, 0
	global_load_dword v2, v1, s[18:19] sc1
	s_waitcnt vmcnt(0)
	v_cmp_eq_u32_e32 vcc, v2, v0
	s_and_saveexec_b64 s[14:15], vcc
	s_cbranch_execz .LBB0_399
	s_add_u32 s16, s8, 0xf101200
	s_addc_u32 s17, s9, 0
	s_mov_b32 s30, 1
	s_mov_b64 s[20:21], 0
	s_branch .LBB0_390

.LBB0_491:
	s_or_b64 exec, exec, s[16:17]
	v_cvt_f32_u32_e32 v5, v3
	s_waitcnt vmcnt(0)
	v_readfirstlane_b32 s14, v4
	v_sub_u32_e32 v4, 0, v3
	v_rcp_iflag_f32_e32 v5, v5
	v_add_u32_e32 v6, s14, v0
	v_mul_f32_e32 v5, 0x4f7ffffe, v5
	v_cvt_u32_f32_e32 v5, v5
	v_mul_lo_u32 v0, v4, v5
	v_mul_hi_u32 v0, v5, v0
	v_add_u32_e32 v0, v5, v0
	v_mul_hi_u32 v0, v6, v0
	v_mul_lo_u32 v4, v0, v3
	v_sub_u32_e32 v4, v6, v4
	v_add_u32_e32 v5, 1, v0
	v_cmp_ge_u32_e32 vcc, v4, v3
	s_nop 1
	v_cndmask_b32_e32 v0, v0, v5, vcc
	v_sub_u32_e32 v5, v4, v3
	v_cndmask_b32_e32 v4, v4, v5, vcc
	v_add_u32_e32 v5, 1, v0
	v_cmp_ge_u32_e32 vcc, v4, v3
	v_add_u32_e32 v4, 1, v6
	s_nop 0
	v_cndmask_b32_e32 v0, v0, v5, vcc
	v_mul_lo_u32 v5, v3, v0
	v_add_u32_e32 v3, v5, v3
	v_cmp_ne_u32_e32 vcc, v4, v3
	s_and_saveexec_b64 s[14:15], vcc
	s_xor_b64 s[14:15], exec, s[14:15]
	s_cbranch_execz .LBB0_505
	s_waitcnt lgkmcnt(0)
	s_add_u32 s20, s10, 0xf104500
	s_addc_u32 s21, s11, 0
	global_load_dword v2, v1, s[20:21] sc1
	s_waitcnt vmcnt(0)
	v_cmp_eq_u32_e32 vcc, v2, v0
	s_and_saveexec_b64 s[16:17], vcc
	s_cbranch_execz .LBB0_504
	s_add_u32 s18, s10, 0xf101200
	s_addc_u32 s19, s11, 0
	s_mov_b32 s34, 1
	s_mov_b64 s[22:23], 0
	s_branch .LBB0_495

.LBB0_628:
	s_or_b64 exec, exec, s[18:19]
	v_cvt_f32_u32_e32 v5, v3
	s_waitcnt vmcnt(0)
	v_readfirstlane_b32 s4, v4
	v_sub_u32_e32 v4, 0, v3
	v_rcp_iflag_f32_e32 v5, v5
	v_add_u32_e32 v6, s4, v0
	v_mul_f32_e32 v5, 0x4f7ffffe, v5
	v_cvt_u32_f32_e32 v5, v5
	v_mul_lo_u32 v0, v4, v5
	v_mul_hi_u32 v0, v5, v0
	v_add_u32_e32 v0, v5, v0
	v_mul_hi_u32 v0, v6, v0
	v_mul_lo_u32 v4, v0, v3
	v_sub_u32_e32 v4, v6, v4
	v_add_u32_e32 v5, 1, v0
	v_cmp_ge_u32_e32 vcc, v4, v3
	s_nop 1
	v_cndmask_b32_e32 v0, v0, v5, vcc
	v_sub_u32_e32 v5, v4, v3
	v_cndmask_b32_e32 v4, v4, v5, vcc
	v_add_u32_e32 v5, 1, v0
	v_cmp_ge_u32_e32 vcc, v4, v3
	v_add_u32_e32 v4, 1, v6
	s_nop 0
	v_cndmask_b32_e32 v0, v0, v5, vcc
	v_mul_lo_u32 v5, v3, v0
	v_add_u32_e32 v3, v5, v3
	v_cmp_ne_u32_e32 vcc, v4, v3
	s_and_saveexec_b64 s[16:17], vcc
	s_xor_b64 s[16:17], exec, s[16:17]
	s_cbranch_execz .LBB0_642
	s_waitcnt lgkmcnt(0)
	s_add_u32 s22, s12, 0xf104500
	s_addc_u32 s23, s13, 0
	global_load_dword v2, v1, s[22:23] sc1
	s_waitcnt vmcnt(0)
	v_cmp_eq_u32_e32 vcc, v2, v0
	s_and_saveexec_b64 s[18:19], vcc
	s_cbranch_execz .LBB0_641
	s_add_u32 s20, s12, 0xf101200
	s_addc_u32 s21, s13, 0
	s_mov_b32 s36, 1
	s_mov_b64 s[24:25], 0
	s_branch .LBB0_632

.LBB0_726:
	s_or_b64 exec, exec, s[16:17]
	v_cvt_f32_u32_e32 v5, v3
	s_waitcnt vmcnt(0)
	v_readfirstlane_b32 s4, v4
	v_sub_u32_e32 v4, 0, v3
	v_rcp_iflag_f32_e32 v5, v5
	v_add_u32_e32 v6, s4, v0
	v_mul_f32_e32 v5, 0x4f7ffffe, v5
	v_cvt_u32_f32_e32 v5, v5
	v_mul_lo_u32 v0, v4, v5
	v_mul_hi_u32 v0, v5, v0
	v_add_u32_e32 v0, v5, v0
	v_mul_hi_u32 v0, v6, v0
	v_mul_lo_u32 v4, v0, v3
	v_sub_u32_e32 v4, v6, v4
	v_add_u32_e32 v5, 1, v0
	v_cmp_ge_u32_e32 vcc, v4, v3
	s_nop 1
	v_cndmask_b32_e32 v0, v0, v5, vcc
	v_sub_u32_e32 v5, v4, v3
	v_cndmask_b32_e32 v4, v4, v5, vcc
	v_add_u32_e32 v5, 1, v0
	v_cmp_ge_u32_e32 vcc, v4, v3
	v_add_u32_e32 v4, 1, v6
	s_nop 0
	v_cndmask_b32_e32 v0, v0, v5, vcc
	v_mul_lo_u32 v5, v3, v0
	v_add_u32_e32 v3, v5, v3
	v_cmp_ne_u32_e32 vcc, v4, v3
	s_and_saveexec_b64 s[14:15], vcc
	s_xor_b64 s[14:15], exec, s[14:15]
	s_cbranch_execz .LBB0_740
	s_waitcnt lgkmcnt(0)
	s_add_u32 s20, s10, 0xf104500
	s_addc_u32 s21, s11, 0
	global_load_dword v2, v1, s[20:21] sc1
	s_waitcnt vmcnt(0)
	v_cmp_eq_u32_e32 vcc, v2, v0
	s_and_saveexec_b64 s[16:17], vcc
	s_cbranch_execz .LBB0_739
	s_add_u32 s18, s10, 0xf101200
	s_addc_u32 s19, s11, 0
	s_mov_b32 s34, 1
	s_mov_b64 s[22:23], 0
	s_branch .LBB0_730

.LBB0_979:
	s_or_b64 exec, exec, s[14:15]
	v_cvt_f32_u32_e32 v5, v3
	s_waitcnt vmcnt(0)
	v_readfirstlane_b32 s4, v4
	v_sub_u32_e32 v4, 0, v3
	v_rcp_iflag_f32_e32 v5, v5
	v_add_u32_e32 v6, s4, v0
	v_mul_f32_e32 v5, 0x4f7ffffe, v5
	v_cvt_u32_f32_e32 v5, v5
	v_mul_lo_u32 v0, v4, v5
	v_mul_hi_u32 v0, v5, v0
	v_add_u32_e32 v0, v5, v0
	v_mul_hi_u32 v0, v6, v0
	v_mul_lo_u32 v4, v0, v3
	v_sub_u32_e32 v4, v6, v4
	v_add_u32_e32 v5, 1, v0
	v_cmp_ge_u32_e32 vcc, v4, v3
	s_nop 1
	v_cndmask_b32_e32 v0, v0, v5, vcc
	v_sub_u32_e32 v5, v4, v3
	v_cndmask_b32_e32 v4, v4, v5, vcc
	v_add_u32_e32 v5, 1, v0
	v_cmp_ge_u32_e32 vcc, v4, v3
	v_add_u32_e32 v4, 1, v6
	s_nop 0
	v_cndmask_b32_e32 v0, v0, v5, vcc
	v_mul_lo_u32 v5, v3, v0
	v_add_u32_e32 v3, v5, v3
	v_cmp_ne_u32_e32 vcc, v4, v3
	s_and_saveexec_b64 s[12:13], vcc
	s_xor_b64 s[12:13], exec, s[12:13]
	s_cbranch_execz .LBB0_993
	s_waitcnt lgkmcnt(0)
	s_add_u32 s18, s8, 0xf104500
	s_addc_u32 s19, s9, 0
	global_load_dword v2, v1, s[18:19] sc1
	s_waitcnt vmcnt(0)
	v_cmp_eq_u32_e32 vcc, v2, v0
	s_and_saveexec_b64 s[14:15], vcc
	s_cbranch_execz .LBB0_992
	s_add_u32 s16, s8, 0xf101200
	s_addc_u32 s17, s9, 0
	s_mov_b32 s30, 1
	s_mov_b64 s[20:21], 0
	s_branch .LBB0_983
